# v56 + nt (streaming) hint on the gate/up epilogue's HID stores
# baseline (speedup 1.0000x reference)
; __device__ __forceinline__ unsigned cvtpk(float lo, float hi) { f32x2 v = {lo, hi}; bf16x2_t b = __builtin_convertvector(v, bf16x2_t); return __builtin_bit_cast(unsigned, b); }
; #define PG8_LAS __attribute__((address_space(3)))
;     __device__ __forceinline__ void operator()(Acc& acc, const Unit& u, int wr, int wc, int fr, int fq, PG8_LAS unsigned char*, const Pre& P) const {
;         const int col0 = u.pn * 128 + wc * 32 + 8 * fq;
; #pragma unroll
;         for (int ai = 0; ai < 2; ++ai)
; #pragma unroll
;             for (int m = 0; m < 4; ++m) {
;                 const int row = u.pm * 256 + ai * 128 + wr * 64 + m * 16 + fr;
;                 const float r2 = rsqrtf(P.r2[ai][m] * (1.0f / DM) + EPS);
;                 float h[8];
; #pragma unroll
;                 for (int n = 0; n < 2; ++n)
; #pragma unroll
;                     for (int j = 0; j < 4; ++j) { const float g = acc[ai][0][m][n][j] * r2 + P.bg[n][j], up = acc[ai][1][m][n][j] * r2 + P.bu[n][j];
;                         h[n * 4 + j] = g * __builtin_amdgcn_rcpf(1.0f + __builtin_amdgcn_exp2f(-g * LOG2E)) * up; }
;                 u32x4 w; w.x = cvtpk(h[0], h[1]); w.y = cvtpk(h[2], h[3]); w.z = cvtpk(h[4], h[5]); w.w = cvtpk(h[6], h[7]);
;                 *(u32x4*)(HID + (size_t)row * FFH + col0) = w;
;             }
;     }
.LBB0_947:
	v_lshl_add_u32 v236, s53, 7, v164
	v_lshl_add_u32 v237, s24, 8, v162
	v_ashrrev_i32_e32 v239, 31, v236
	v_mov_b32_e32 v238, v236
	v_mov_b64_e32 v[232:233], s[12:13]
	v_mad_i64_i32 v[232:233], s[26:27], v237, s52, v[232:233]
	v_lshlrev_b64 v[238:239], 1, v[238:239]
	v_mov_b32_e32 v178, 0xbfb8aa3b
	s_mov_b32 s62, 0x16000
	s_mov_b32 s63, 0
	s_mov_b32 s66, 0x6e000
	s_mov_b32 s67, 0
	v_lshl_add_u64 v[232:233], v[232:233], 0, v[238:239]
	v_fmamk_f32 v176, v174, 0x3a800000, v166
	v_rsq_f32_e32 v176, v176
	s_nop 0
	v_pk_fma_f32 v[180:181], v[176:177], v[140:141], v[12:13] op_sel_hi:[0,1,1]
	v_pk_fma_f32 v[182:183], v[176:177], v[142:143], v[14:15] op_sel_hi:[0,1,1]
	v_pk_fma_f32 v[184:185], v[176:177], v[136:137], v[4:5] op_sel_hi:[0,1,1]
	v_pk_fma_f32 v[186:187], v[176:177], v[138:139], v[6:7] op_sel_hi:[0,1,1]
	v_pk_fma_f32 v[188:189], v[176:177], v[132:133], v[8:9] op_sel_hi:[0,1,1]
	v_pk_fma_f32 v[190:191], v[176:177], v[134:135], v[10:11] op_sel_hi:[0,1,1]
	v_pk_fma_f32 v[192:193], v[176:177], v[128:129], v[0:1] op_sel_hi:[0,1,1]
	v_pk_fma_f32 v[194:195], v[176:177], v[130:131], v[2:3] op_sel_hi:[0,1,1]
	v_pk_mul_f32 v[196:197], v[180:181], v[178:179] op_sel_hi:[1,0]
	v_pk_mul_f32 v[198:199], v[182:183], v[178:179] op_sel_hi:[1,0]
	v_pk_mul_f32 v[200:201], v[184:185], v[178:179] op_sel_hi:[1,0]
	v_pk_mul_f32 v[202:203], v[186:187], v[178:179] op_sel_hi:[1,0]
	v_exp_f32_e32 v196, v196
	v_exp_f32_e32 v197, v197
	v_exp_f32_e32 v198, v198
	v_exp_f32_e32 v199, v199
	v_exp_f32_e32 v200, v200
	v_exp_f32_e32 v201, v201
	v_exp_f32_e32 v202, v202
	v_exp_f32_e32 v203, v203
	v_pk_add_f32 v[196:197], v[196:197], 1.0 op_sel_hi:[1,0]
	v_pk_add_f32 v[198:199], v[198:199], 1.0 op_sel_hi:[1,0]
	v_pk_add_f32 v[200:201], v[200:201], 1.0 op_sel_hi:[1,0]
	v_pk_add_f32 v[202:203], v[202:203], 1.0 op_sel_hi:[1,0]
	v_rcp_f32_e32 v196, v196
	v_rcp_f32_e32 v197, v197
	v_rcp_f32_e32 v198, v198
	v_rcp_f32_e32 v199, v199
	v_rcp_f32_e32 v200, v200
	v_rcp_f32_e32 v201, v201
	v_rcp_f32_e32 v202, v202
	v_rcp_f32_e32 v203, v203
	v_pk_mul_f32 v[180:181], v[180:181], v[196:197]
	v_pk_mul_f32 v[182:183], v[182:183], v[198:199]
	v_pk_mul_f32 v[184:185], v[184:185], v[200:201]
	v_pk_mul_f32 v[186:187], v[186:187], v[202:203]
	v_pk_mul_f32 v[180:181], v[180:181], v[188:189]
	v_pk_mul_f32 v[182:183], v[182:183], v[190:191]
	v_pk_mul_f32 v[184:185], v[184:185], v[192:193]
	v_pk_mul_f32 v[186:187], v[186:187], v[194:195]
	v_cvt_pk_bf16_f32 v244, v180, v181
	v_cvt_pk_bf16_f32 v245, v182, v183
	v_cvt_pk_bf16_f32 v246, v184, v185
	v_cvt_pk_bf16_f32 v247, v186, v187
	global_store_dwordx4 v[232:233], v[244:247], off nt
	v_lshl_add_u64 v[232:233], v[232:233], 0, s[62:63]
	v_fmamk_f32 v204, v173, 0x3a800000, v166
	v_rsq_f32_e32 v204, v204
	s_nop 0
	v_pk_fma_f32 v[208:209], v[204:205], v[124:125], v[12:13] op_sel_hi:[0,1,1]
	v_pk_fma_f32 v[210:211], v[204:205], v[126:127], v[14:15] op_sel_hi:[0,1,1]
	v_pk_fma_f32 v[212:213], v[204:205], v[120:121], v[4:5] op_sel_hi:[0,1,1]
	v_pk_fma_f32 v[214:215], v[204:205], v[122:123], v[6:7] op_sel_hi:[0,1,1]
	v_pk_fma_f32 v[216:217], v[204:205], v[116:117], v[8:9] op_sel_hi:[0,1,1]
	v_pk_fma_f32 v[218:219], v[204:205], v[118:119], v[10:11] op_sel_hi:[0,1,1]
	v_pk_fma_f32 v[220:221], v[204:205], v[112:113], v[0:1] op_sel_hi:[0,1,1]
	v_pk_fma_f32 v[222:223], v[204:205], v[114:115], v[2:3] op_sel_hi:[0,1,1]
	v_pk_mul_f32 v[224:225], v[208:209], v[178:179] op_sel_hi:[1,0]
	v_pk_mul_f32 v[226:227], v[210:211], v[178:179] op_sel_hi:[1,0]
	v_pk_mul_f32 v[228:229], v[212:213], v[178:179] op_sel_hi:[1,0]
	v_pk_mul_f32 v[230:231], v[214:215], v[178:179] op_sel_hi:[1,0]
	v_exp_f32_e32 v224, v224
	v_exp_f32_e32 v225, v225
	v_exp_f32_e32 v226, v226
	v_exp_f32_e32 v227, v227
	v_exp_f32_e32 v228, v228
	v_exp_f32_e32 v229, v229
	v_exp_f32_e32 v230, v230
	v_exp_f32_e32 v231, v231
	v_pk_add_f32 v[224:225], v[224:225], 1.0 op_sel_hi:[1,0]
	v_pk_add_f32 v[226:227], v[226:227], 1.0 op_sel_hi:[1,0]
	v_pk_add_f32 v[228:229], v[228:229], 1.0 op_sel_hi:[1,0]
	v_pk_add_f32 v[230:231], v[230:231], 1.0 op_sel_hi:[1,0]
	v_rcp_f32_e32 v224, v224
	v_rcp_f32_e32 v225, v225
	v_rcp_f32_e32 v226, v226
	v_rcp_f32_e32 v227, v227
	v_rcp_f32_e32 v228, v228
	v_rcp_f32_e32 v229, v229
	v_rcp_f32_e32 v230, v230
	v_rcp_f32_e32 v231, v231
	v_pk_mul_f32 v[208:209], v[208:209], v[224:225]
	v_pk_mul_f32 v[210:211], v[210:211], v[226:227]
	v_pk_mul_f32 v[212:213], v[212:213], v[228:229]
	v_pk_mul_f32 v[214:215], v[214:215], v[230:231]
	v_pk_mul_f32 v[208:209], v[208:209], v[216:217]
	v_pk_mul_f32 v[210:211], v[210:211], v[218:219]
	v_pk_mul_f32 v[212:213], v[212:213], v[220:221]
	v_pk_mul_f32 v[214:215], v[214:215], v[222:223]
	v_cvt_pk_bf16_f32 v248, v208, v209
	v_cvt_pk_bf16_f32 v249, v210, v211
	v_cvt_pk_bf16_f32 v250, v212, v213
	v_cvt_pk_bf16_f32 v251, v214, v215
	global_store_dwordx4 v[232:233], v[248:251], off nt
	v_lshl_add_u64 v[232:233], v[232:233], 0, s[62:63]
	v_fmamk_f32 v176, v172, 0x3a800000, v166
	v_rsq_f32_e32 v176, v176
	s_nop 0
	v_pk_fma_f32 v[180:181], v[176:177], v[108:109], v[12:13] op_sel_hi:[0,1,1]
	v_pk_fma_f32 v[182:183], v[176:177], v[110:111], v[14:15] op_sel_hi:[0,1,1]
	v_pk_fma_f32 v[184:185], v[176:177], v[104:105], v[4:5] op_sel_hi:[0,1,1]
	v_pk_fma_f32 v[186:187], v[176:177], v[106:107], v[6:7] op_sel_hi:[0,1,1]
	v_pk_fma_f32 v[188:189], v[176:177], v[100:101], v[8:9] op_sel_hi:[0,1,1]
	v_pk_fma_f32 v[190:191], v[176:177], v[102:103], v[10:11] op_sel_hi:[0,1,1]
	v_pk_fma_f32 v[192:193], v[176:177], v[96:97], v[0:1] op_sel_hi:[0,1,1]
	v_pk_fma_f32 v[194:195], v[176:177], v[98:99], v[2:3] op_sel_hi:[0,1,1]
	v_pk_mul_f32 v[196:197], v[180:181], v[178:179] op_sel_hi:[1,0]
; __device__ __forceinline__ unsigned cvtpk(float lo, float hi) { f32x2 v = {lo, hi}; bf16x2_t b = __builtin_convertvector(v, bf16x2_t); return __builtin_bit_cast(unsigned, b); }
; #define PG8_LAS __attribute__((address_space(3)))
;     __device__ __forceinline__ void operator()(Acc& acc, const Unit& u, int wr, int wc, int fr, int fq, PG8_LAS unsigned char*, const Pre& P) const {
;         const int col0 = u.pn * 128 + wc * 32 + 8 * fq;
; #pragma unroll
;         for (int ai = 0; ai < 2; ++ai)
; #pragma unroll
;             for (int m = 0; m < 4; ++m) {
;                 const int row = u.pm * 256 + ai * 128 + wr * 64 + m * 16 + fr;
;                 const float r2 = rsqrtf(P.r2[ai][m] * (1.0f / DM) + EPS);
;                 float h[8];
; #pragma unroll
;                 for (int n = 0; n < 2; ++n)
; #pragma unroll
;                     for (int j = 0; j < 4; ++j) { const float g = acc[ai][0][m][n][j] * r2 + P.bg[n][j], up = acc[ai][1][m][n][j] * r2 + P.bu[n][j];
;                         h[n * 4 + j] = g * __builtin_amdgcn_rcpf(1.0f + __builtin_amdgcn_exp2f(-g * LOG2E)) * up; }
;                 u32x4 w; w.x = cvtpk(h[0], h[1]); w.y = cvtpk(h[2], h[3]); w.z = cvtpk(h[4], h[5]); w.w = cvtpk(h[6], h[7]);
;                 *(u32x4*)(HID + (size_t)row * FFH + col0) = w;
;             }
;     }
	v_pk_mul_f32 v[198:199], v[182:183], v[178:179] op_sel_hi:[1,0]
	v_pk_mul_f32 v[200:201], v[184:185], v[178:179] op_sel_hi:[1,0]
	v_pk_mul_f32 v[202:203], v[186:187], v[178:179] op_sel_hi:[1,0]
	v_exp_f32_e32 v196, v196
	v_exp_f32_e32 v197, v197
	v_exp_f32_e32 v198, v198
	v_exp_f32_e32 v199, v199
	v_exp_f32_e32 v200, v200
	v_exp_f32_e32 v201, v201
	v_exp_f32_e32 v202, v202
	v_exp_f32_e32 v203, v203
	v_pk_add_f32 v[196:197], v[196:197], 1.0 op_sel_hi:[1,0]
	v_pk_add_f32 v[198:199], v[198:199], 1.0 op_sel_hi:[1,0]
	v_pk_add_f32 v[200:201], v[200:201], 1.0 op_sel_hi:[1,0]
	v_pk_add_f32 v[202:203], v[202:203], 1.0 op_sel_hi:[1,0]
	v_rcp_f32_e32 v196, v196
	v_rcp_f32_e32 v197, v197
	v_rcp_f32_e32 v198, v198
	v_rcp_f32_e32 v199, v199
	v_rcp_f32_e32 v200, v200
	v_rcp_f32_e32 v201, v201
	v_rcp_f32_e32 v202, v202
	v_rcp_f32_e32 v203, v203
	v_pk_mul_f32 v[180:181], v[180:181], v[196:197]
	v_pk_mul_f32 v[182:183], v[182:183], v[198:199]
	v_pk_mul_f32 v[184:185], v[184:185], v[200:201]
	v_pk_mul_f32 v[186:187], v[186:187], v[202:203]
	v_pk_mul_f32 v[180:181], v[180:181], v[188:189]
	v_pk_mul_f32 v[182:183], v[182:183], v[190:191]
	v_pk_mul_f32 v[184:185], v[184:185], v[192:193]
	v_pk_mul_f32 v[186:187], v[186:187], v[194:195]
	v_cvt_pk_bf16_f32 v244, v180, v181
	v_cvt_pk_bf16_f32 v245, v182, v183
	v_cvt_pk_bf16_f32 v246, v184, v185
	v_cvt_pk_bf16_f32 v247, v186, v187
	global_store_dwordx4 v[232:233], v[244:247], off nt
	v_lshl_add_u64 v[232:233], v[232:233], 0, s[62:63]
	v_fmamk_f32 v204, v171, 0x3a800000, v166
	v_rsq_f32_e32 v204, v204
	s_nop 0
	v_pk_fma_f32 v[208:209], v[204:205], v[92:93], v[12:13] op_sel_hi:[0,1,1]
	v_pk_fma_f32 v[210:211], v[204:205], v[94:95], v[14:15] op_sel_hi:[0,1,1]
	v_pk_fma_f32 v[212:213], v[204:205], v[88:89], v[4:5] op_sel_hi:[0,1,1]
	v_pk_fma_f32 v[214:215], v[204:205], v[90:91], v[6:7] op_sel_hi:[0,1,1]
	v_pk_fma_f32 v[216:217], v[204:205], v[84:85], v[8:9] op_sel_hi:[0,1,1]
	v_pk_fma_f32 v[218:219], v[204:205], v[86:87], v[10:11] op_sel_hi:[0,1,1]
	v_pk_fma_f32 v[220:221], v[204:205], v[80:81], v[0:1] op_sel_hi:[0,1,1]
	v_pk_fma_f32 v[222:223], v[204:205], v[82:83], v[2:3] op_sel_hi:[0,1,1]
	v_pk_mul_f32 v[224:225], v[208:209], v[178:179] op_sel_hi:[1,0]
	v_pk_mul_f32 v[226:227], v[210:211], v[178:179] op_sel_hi:[1,0]
	v_pk_mul_f32 v[228:229], v[212:213], v[178:179] op_sel_hi:[1,0]
	v_pk_mul_f32 v[230:231], v[214:215], v[178:179] op_sel_hi:[1,0]
	v_exp_f32_e32 v224, v224
	v_exp_f32_e32 v225, v225
	v_exp_f32_e32 v226, v226
	v_exp_f32_e32 v227, v227
	v_exp_f32_e32 v228, v228
	v_exp_f32_e32 v229, v229
	v_exp_f32_e32 v230, v230
	v_exp_f32_e32 v231, v231
	v_pk_add_f32 v[224:225], v[224:225], 1.0 op_sel_hi:[1,0]
	v_pk_add_f32 v[226:227], v[226:227], 1.0 op_sel_hi:[1,0]
	v_pk_add_f32 v[228:229], v[228:229], 1.0 op_sel_hi:[1,0]
	v_pk_add_f32 v[230:231], v[230:231], 1.0 op_sel_hi:[1,0]
	v_rcp_f32_e32 v224, v224
	v_rcp_f32_e32 v225, v225
	v_rcp_f32_e32 v226, v226
	v_rcp_f32_e32 v227, v227
	v_rcp_f32_e32 v228, v228
	v_rcp_f32_e32 v229, v229
	v_rcp_f32_e32 v230, v230
	v_rcp_f32_e32 v231, v231
	v_pk_mul_f32 v[208:209], v[208:209], v[224:225]
	v_pk_mul_f32 v[210:211], v[210:211], v[226:227]
	v_pk_mul_f32 v[212:213], v[212:213], v[228:229]
	v_pk_mul_f32 v[214:215], v[214:215], v[230:231]
	v_pk_mul_f32 v[208:209], v[208:209], v[216:217]
	v_pk_mul_f32 v[210:211], v[210:211], v[218:219]
	v_pk_mul_f32 v[212:213], v[212:213], v[220:221]
	v_pk_mul_f32 v[214:215], v[214:215], v[222:223]
	v_cvt_pk_bf16_f32 v248, v208, v209
	v_cvt_pk_bf16_f32 v249, v210, v211
	v_cvt_pk_bf16_f32 v250, v212, v213
	v_cvt_pk_bf16_f32 v251, v214, v215
	global_store_dwordx4 v[232:233], v[248:251], off nt
	v_lshl_add_u64 v[232:233], v[232:233], 0, s[66:67]
	v_fmamk_f32 v176, v170, 0x3a800000, v166
	v_rsq_f32_e32 v176, v176
	s_nop 0
	v_pk_fma_f32 v[180:181], v[176:177], v[76:77], v[12:13] op_sel_hi:[0,1,1]
	v_pk_fma_f32 v[182:183], v[176:177], v[78:79], v[14:15] op_sel_hi:[0,1,1]
	v_pk_fma_f32 v[184:185], v[176:177], v[72:73], v[4:5] op_sel_hi:[0,1,1]
	v_pk_fma_f32 v[186:187], v[176:177], v[74:75], v[6:7] op_sel_hi:[0,1,1]
	v_pk_fma_f32 v[188:189], v[176:177], v[68:69], v[8:9] op_sel_hi:[0,1,1]
	v_pk_fma_f32 v[190:191], v[176:177], v[70:71], v[10:11] op_sel_hi:[0,1,1]
	v_pk_fma_f32 v[192:193], v[176:177], v[64:65], v[0:1] op_sel_hi:[0,1,1]
	v_pk_fma_f32 v[194:195], v[176:177], v[66:67], v[2:3] op_sel_hi:[0,1,1]
	v_pk_mul_f32 v[196:197], v[180:181], v[178:179] op_sel_hi:[1,0]
	v_pk_mul_f32 v[198:199], v[182:183], v[178:179] op_sel_hi:[1,0]
	v_pk_mul_f32 v[200:201], v[184:185], v[178:179] op_sel_hi:[1,0]
	v_pk_mul_f32 v[202:203], v[186:187], v[178:179] op_sel_hi:[1,0]
	v_exp_f32_e32 v196, v196
	v_exp_f32_e32 v197, v197
	v_exp_f32_e32 v198, v198
	v_exp_f32_e32 v199, v199
	v_exp_f32_e32 v200, v200
	v_exp_f32_e32 v201, v201
	v_exp_f32_e32 v202, v202
	v_exp_f32_e32 v203, v203
	v_pk_add_f32 v[196:197], v[196:197], 1.0 op_sel_hi:[1,0]
	v_pk_add_f32 v[198:199], v[198:199], 1.0 op_sel_hi:[1,0]
	v_pk_add_f32 v[200:201], v[200:201], 1.0 op_sel_hi:[1,0]
	v_pk_add_f32 v[202:203], v[202:203], 1.0 op_sel_hi:[1,0]
	v_rcp_f32_e32 v196, v196
	v_rcp_f32_e32 v197, v197
	v_rcp_f32_e32 v198, v198
	v_rcp_f32_e32 v199, v199
	v_rcp_f32_e32 v200, v200
	v_rcp_f32_e32 v201, v201
	v_rcp_f32_e32 v202, v202
	v_rcp_f32_e32 v203, v203
	v_pk_mul_f32 v[180:181], v[180:181], v[196:197]
	v_pk_mul_f32 v[182:183], v[182:183], v[198:199]
	v_pk_mul_f32 v[184:185], v[184:185], v[200:201]
	v_pk_mul_f32 v[186:187], v[186:187], v[202:203]
	v_pk_mul_f32 v[180:181], v[180:181], v[188:189]
	v_pk_mul_f32 v[182:183], v[182:183], v[190:191]
	v_pk_mul_f32 v[184:185], v[184:185], v[192:193]
; #define PG8_LAS __attribute__((address_space(3)))
;     __device__ __forceinline__ void operator()(Acc& acc, const Unit& u, int wr, int wc, int fr, int fq, PG8_LAS unsigned char*, const Pre& P) const {
;         const int col0 = u.pn * 128 + wc * 32 + 8 * fq;
; #pragma unroll
;         for (int ai = 0; ai < 2; ++ai)
; #pragma unroll
;             for (int m = 0; m < 4; ++m) {
;                 const int row = u.pm * 256 + ai * 128 + wr * 64 + m * 16 + fr;
;                 const float r2 = rsqrtf(P.r2[ai][m] * (1.0f / DM) + EPS);
;                 float h[8];
; #pragma unroll
;                 for (int n = 0; n < 2; ++n)
; #pragma unroll
;                     for (int j = 0; j < 4; ++j) { const float g = acc[ai][0][m][n][j] * r2 + P.bg[n][j], up = acc[ai][1][m][n][j] * r2 + P.bu[n][j];
;                         h[n * 4 + j] = g * __builtin_amdgcn_rcpf(1.0f + __builtin_amdgcn_exp2f(-g * LOG2E)) * up; }
;                 u32x4 w; w.x = cvtpk(h[0], h[1]); w.y = cvtpk(h[2], h[3]); w.z = cvtpk(h[4], h[5]); w.w = cvtpk(h[6], h[7]);
;                 *(u32x4*)(HID + (size_t)row * FFH + col0) = w;
;             }
;     }
; template <class Epi, class Sched>
; __device__ __forceinline__ void gemm_phase(PG8_LAS unsigned char* lds, PG8_LAS unsigned char* ldx, const Gemm g, const Sched& S, const Epi& E, const int wid) {
;     ...
;         const bool has_next = S.next(ui + 1, nxt);
;         const char* nA = has_next ? (const char*)g.A + (size_t)nxt.pm * tstep : cA; const char* nB = has_next ? (const char*)g.Bt + (size_t)nxt.pn * tstep : cB;
;         for (int t = 0; t < nt; t += 2) {
;             const bool last = (t == nt - 2);
;             const char* a1 = cA + (size_t)(t + 1) * kstep;
;             const char* a2 = last ? nA : cA + (size_t)(t + 2) * kstep; const char* b2 = last ? nB : cB + (size_t)(t + 2) * kstep;
;             const char* a3 = a2 + kstep; const char* b3 = b2 + kstep;
;             if constexpr (Epi::HAS_MID) { if (t == (nt >> 1)) E.mid(acc, cur, wr, wc, fr, fq); }
;             PG8_LDB(B0, 0, 0); PG8_LDB(B1, 0, 1); PG8_SCHED; PG8_LDA(At, 0, 0); PG8_STAGE(PG8_SA(1, 1), a1 + hstep, voffA);
;             PG8_WAIT_V(8); PG8_WAIT_L(0); PG8_BAR; PG8_MMA(0, 0, At, B0); PG8_MMA(0, 1, At, B1); PG8_BAR; PG8_SCHED;
;             PG8_LDA(At, 0, 1); PG8_STAGE(PG8_SB(0, 0), b2, voffB); PG8_STAGE(PG8_SB(0, 1), b2 + hstep, voffB); PG8_STAGE(PG8_SA(0, 0), a2, voffA);
	v_pk_mul_f32 v[186:187], v[186:187], v[194:195]
	v_cvt_pk_bf16_f32 v244, v180, v181
	v_cvt_pk_bf16_f32 v245, v182, v183
	v_cvt_pk_bf16_f32 v246, v184, v185
	v_cvt_pk_bf16_f32 v247, v186, v187
	global_store_dwordx4 v[232:233], v[244:247], off nt
	v_lshl_add_u64 v[232:233], v[232:233], 0, s[62:63]
	v_fmamk_f32 v204, v169, 0x3a800000, v166
	v_rsq_f32_e32 v204, v204
	s_nop 0
	v_pk_fma_f32 v[208:209], v[204:205], v[60:61], v[12:13] op_sel_hi:[0,1,1]
	v_pk_fma_f32 v[210:211], v[204:205], v[62:63], v[14:15] op_sel_hi:[0,1,1]
	v_pk_fma_f32 v[212:213], v[204:205], v[56:57], v[4:5] op_sel_hi:[0,1,1]
	v_pk_fma_f32 v[214:215], v[204:205], v[58:59], v[6:7] op_sel_hi:[0,1,1]
	v_pk_fma_f32 v[216:217], v[204:205], v[52:53], v[8:9] op_sel_hi:[0,1,1]
	v_pk_fma_f32 v[218:219], v[204:205], v[54:55], v[10:11] op_sel_hi:[0,1,1]
	v_pk_fma_f32 v[220:221], v[204:205], v[48:49], v[0:1] op_sel_hi:[0,1,1]
	v_pk_fma_f32 v[222:223], v[204:205], v[50:51], v[2:3] op_sel_hi:[0,1,1]
	v_pk_mul_f32 v[224:225], v[208:209], v[178:179] op_sel_hi:[1,0]
	v_pk_mul_f32 v[226:227], v[210:211], v[178:179] op_sel_hi:[1,0]
	v_pk_mul_f32 v[228:229], v[212:213], v[178:179] op_sel_hi:[1,0]
	v_pk_mul_f32 v[230:231], v[214:215], v[178:179] op_sel_hi:[1,0]
	v_exp_f32_e32 v224, v224
	v_exp_f32_e32 v225, v225
	v_exp_f32_e32 v226, v226
	v_exp_f32_e32 v227, v227
	v_exp_f32_e32 v228, v228
	v_exp_f32_e32 v229, v229
	v_exp_f32_e32 v230, v230
	v_exp_f32_e32 v231, v231
	v_pk_add_f32 v[224:225], v[224:225], 1.0 op_sel_hi:[1,0]
	v_pk_add_f32 v[226:227], v[226:227], 1.0 op_sel_hi:[1,0]
	v_pk_add_f32 v[228:229], v[228:229], 1.0 op_sel_hi:[1,0]
	v_pk_add_f32 v[230:231], v[230:231], 1.0 op_sel_hi:[1,0]
	v_rcp_f32_e32 v224, v224
	v_rcp_f32_e32 v225, v225
	v_rcp_f32_e32 v226, v226
	v_rcp_f32_e32 v227, v227
	v_rcp_f32_e32 v228, v228
	v_rcp_f32_e32 v229, v229
	v_rcp_f32_e32 v230, v230
	v_rcp_f32_e32 v231, v231
	v_pk_mul_f32 v[208:209], v[208:209], v[224:225]
	v_pk_mul_f32 v[210:211], v[210:211], v[226:227]
	v_pk_mul_f32 v[212:213], v[212:213], v[228:229]
	v_pk_mul_f32 v[214:215], v[214:215], v[230:231]
	v_pk_mul_f32 v[208:209], v[208:209], v[216:217]
	v_pk_mul_f32 v[210:211], v[210:211], v[218:219]
	v_pk_mul_f32 v[212:213], v[212:213], v[220:221]
	v_pk_mul_f32 v[214:215], v[214:215], v[222:223]
	v_cvt_pk_bf16_f32 v248, v208, v209
	v_cvt_pk_bf16_f32 v249, v210, v211
	v_cvt_pk_bf16_f32 v250, v212, v213
	v_cvt_pk_bf16_f32 v251, v214, v215
	global_store_dwordx4 v[232:233], v[248:251], off nt
	v_lshl_add_u64 v[232:233], v[232:233], 0, s[62:63]
	v_fmamk_f32 v176, v168, 0x3a800000, v166
	v_rsq_f32_e32 v176, v176
	s_nop 0
	v_pk_fma_f32 v[180:181], v[176:177], v[44:45], v[12:13] op_sel_hi:[0,1,1]
	v_pk_fma_f32 v[182:183], v[176:177], v[46:47], v[14:15] op_sel_hi:[0,1,1]
	v_pk_fma_f32 v[184:185], v[176:177], v[40:41], v[4:5] op_sel_hi:[0,1,1]
	v_pk_fma_f32 v[186:187], v[176:177], v[42:43], v[6:7] op_sel_hi:[0,1,1]
	v_pk_fma_f32 v[188:189], v[176:177], v[36:37], v[8:9] op_sel_hi:[0,1,1]
	v_pk_fma_f32 v[190:191], v[176:177], v[38:39], v[10:11] op_sel_hi:[0,1,1]
	v_pk_fma_f32 v[192:193], v[176:177], v[32:33], v[0:1] op_sel_hi:[0,1,1]
	v_pk_fma_f32 v[194:195], v[176:177], v[34:35], v[2:3] op_sel_hi:[0,1,1]
	v_pk_mul_f32 v[196:197], v[180:181], v[178:179] op_sel_hi:[1,0]
	v_pk_mul_f32 v[198:199], v[182:183], v[178:179] op_sel_hi:[1,0]
	v_pk_mul_f32 v[200:201], v[184:185], v[178:179] op_sel_hi:[1,0]
	v_pk_mul_f32 v[202:203], v[186:187], v[178:179] op_sel_hi:[1,0]
	v_exp_f32_e32 v196, v196
	v_exp_f32_e32 v197, v197
	v_exp_f32_e32 v198, v198
	v_exp_f32_e32 v199, v199
	v_exp_f32_e32 v200, v200
	v_exp_f32_e32 v201, v201
	v_exp_f32_e32 v202, v202
	v_exp_f32_e32 v203, v203
	v_pk_add_f32 v[196:197], v[196:197], 1.0 op_sel_hi:[1,0]
	v_pk_add_f32 v[198:199], v[198:199], 1.0 op_sel_hi:[1,0]
	v_pk_add_f32 v[200:201], v[200:201], 1.0 op_sel_hi:[1,0]
	v_pk_add_f32 v[202:203], v[202:203], 1.0 op_sel_hi:[1,0]
	v_rcp_f32_e32 v196, v196
	v_rcp_f32_e32 v197, v197
	v_rcp_f32_e32 v198, v198
	v_rcp_f32_e32 v199, v199
	v_rcp_f32_e32 v200, v200
	v_rcp_f32_e32 v201, v201
	v_rcp_f32_e32 v202, v202
	v_rcp_f32_e32 v203, v203
	v_pk_mul_f32 v[180:181], v[180:181], v[196:197]
	v_pk_mul_f32 v[182:183], v[182:183], v[198:199]
	v_pk_mul_f32 v[184:185], v[184:185], v[200:201]
	v_pk_mul_f32 v[186:187], v[186:187], v[202:203]
	v_pk_mul_f32 v[180:181], v[180:181], v[188:189]
	v_pk_mul_f32 v[182:183], v[182:183], v[190:191]
	v_pk_mul_f32 v[184:185], v[184:185], v[192:193]
	v_pk_mul_f32 v[186:187], v[186:187], v[194:195]
	v_cvt_pk_bf16_f32 v244, v180, v181
	v_cvt_pk_bf16_f32 v245, v182, v183
	v_cvt_pk_bf16_f32 v246, v184, v185
	v_cvt_pk_bf16_f32 v247, v186, v187
	global_store_dwordx4 v[232:233], v[244:247], off nt
	v_lshl_add_u64 v[232:233], v[232:233], 0, s[62:63]
	v_fmamk_f32 v204, v167, 0x3a800000, v166
	v_rsq_f32_e32 v204, v204
	s_nop 0
	v_pk_fma_f32 v[208:209], v[204:205], v[28:29], v[12:13] op_sel_hi:[0,1,1]
	v_pk_fma_f32 v[210:211], v[204:205], v[30:31], v[14:15] op_sel_hi:[0,1,1]
	v_pk_fma_f32 v[212:213], v[204:205], v[24:25], v[4:5] op_sel_hi:[0,1,1]
	v_pk_fma_f32 v[214:215], v[204:205], v[26:27], v[6:7] op_sel_hi:[0,1,1]
	v_pk_fma_f32 v[216:217], v[204:205], v[20:21], v[8:9] op_sel_hi:[0,1,1]
	v_pk_fma_f32 v[218:219], v[204:205], v[22:23], v[10:11] op_sel_hi:[0,1,1]
	v_pk_fma_f32 v[220:221], v[204:205], v[16:17], v[0:1] op_sel_hi:[0,1,1]
	v_pk_fma_f32 v[222:223], v[204:205], v[18:19], v[2:3] op_sel_hi:[0,1,1]
	v_pk_mul_f32 v[224:225], v[208:209], v[178:179] op_sel_hi:[1,0]
	v_pk_mul_f32 v[226:227], v[210:211], v[178:179] op_sel_hi:[1,0]
	v_pk_mul_f32 v[228:229], v[212:213], v[178:179] op_sel_hi:[1,0]
	v_pk_mul_f32 v[230:231], v[214:215], v[178:179] op_sel_hi:[1,0]
	v_exp_f32_e32 v224, v224
	v_exp_f32_e32 v225, v225
	v_exp_f32_e32 v226, v226
	v_exp_f32_e32 v227, v227
	v_exp_f32_e32 v228, v228
	v_exp_f32_e32 v229, v229
	v_exp_f32_e32 v230, v230
	v_exp_f32_e32 v231, v231
	v_pk_add_f32 v[224:225], v[224:225], 1.0 op_sel_hi:[1,0]
	v_pk_add_f32 v[226:227], v[226:227], 1.0 op_sel_hi:[1,0]
	v_pk_add_f32 v[228:229], v[228:229], 1.0 op_sel_hi:[1,0]
	v_pk_add_f32 v[230:231], v[230:231], 1.0 op_sel_hi:[1,0]
	v_rcp_f32_e32 v224, v224
	v_rcp_f32_e32 v225, v225
	v_rcp_f32_e32 v226, v226
	v_rcp_f32_e32 v227, v227
	v_rcp_f32_e32 v228, v228
	v_rcp_f32_e32 v229, v229
	v_rcp_f32_e32 v230, v230
	v_rcp_f32_e32 v231, v231
	v_pk_mul_f32 v[208:209], v[208:209], v[224:225]
	v_pk_mul_f32 v[210:211], v[210:211], v[226:227]
	v_pk_mul_f32 v[212:213], v[212:213], v[228:229]
	v_pk_mul_f32 v[214:215], v[214:215], v[230:231]
	v_pk_mul_f32 v[208:209], v[208:209], v[216:217]
	v_pk_mul_f32 v[210:211], v[210:211], v[218:219]
	v_pk_mul_f32 v[212:213], v[212:213], v[220:221]
	v_pk_mul_f32 v[214:215], v[214:215], v[222:223]
	v_cvt_pk_bf16_f32 v248, v208, v209
	v_cvt_pk_bf16_f32 v249, v210, v211
	v_cvt_pk_bf16_f32 v250, v212, v213
	v_cvt_pk_bf16_f32 v251, v214, v215
	global_store_dwordx4 v[232:233], v[248:251], off nt
	s_andn2_b64 vcc, exec, s[2:3]
	s_mov_b64 s[2:3], -1
	s_cbranch_vccnz .LBB0_940
; #define PG8_BAR __builtin_amdgcn_s_barrier()
;     __device__ __forceinline__ void prefetch(Pre& P, const Unit& u, int wr, int wc, int fr, int fq) const {
;         const float* bp = beta + (size_t)((u.pm * 256) >> 12) * (2 * FFH) + u.pn * 256 + wc * 32 + 8 * fq;
; #pragma unroll
;         for (int n = 0; n < 2; ++n) { P.bg[n] = *(const f32x4*)(bp + 4 * n); P.bu[n] = *(const f32x4*)(bp + 128 + 4 * n); }
; #pragma unroll
;         for (int ai = 0; ai < 2; ++ai)
; #pragma unroll
;             for (int m = 0; m < 4; ++m) P.r2[ai][m] = ssq2[u.pm * 256 + ai * 128 + wr * 64 + m * 16 + fr];
;     }
; template <class Epi, class Sched>
; __device__ __forceinline__ void gemm_phase(PG8_LAS unsigned char* lds, PG8_LAS unsigned char* ldx, const Gemm g, const Sched& S, const Epi& E, const int wid) {
;     ...
;         E.prefetch(pre, cur, wr, wc, fr, fq);
;         if (wr == 1) PG8_BAR;
	s_ashr_i32 s2, s18, 4
	s_mul_hi_i32 s3, s2, 0x5800
	s_mulk_i32 s2, 0x5800
	s_add_u32 s17, s37, s2
	s_addc_u32 s19, s38, s3
	s_lshl_b32 s2, s16, 8
	s_ashr_i32 s3, s2, 31
	s_lshl_b64 s[2:3], s[2:3], 2
	s_add_u32 s2, s17, s2
	s_addc_u32 s3, s19, s3
	v_lshl_add_u32 v16, s18, 8, v162
	s_add_u32 s2, s2, s25
	v_ashrrev_i32_e32 v17, 31, v16
	s_addc_u32 s3, s3, 0
	v_lshl_add_u64 v[18:19], v[16:17], 2, s[8:9]
	v_add_u32_e32 v20, 0x80, v16
	v_add_u32_e32 v22, 0x90, v16
	v_add_u32_e32 v24, 0xa0, v16
	v_add_u32_e32 v16, 0xb0, v16
	v_lshl_add_u64 v[8:9], v[144:145], 2, s[2:3]
	v_ashrrev_i32_e32 v21, 31, v20
	v_ashrrev_i32_e32 v23, 31, v22
	v_ashrrev_i32_e32 v25, 31, v24
	v_ashrrev_i32_e32 v17, 31, v16
	global_load_dwordx4 v[4:7], v[8:9], off offset:16
	global_load_dwordx4 v[12:15], v[8:9], off
	global_load_dwordx4 v[0:3], v[8:9], off offset:528
	s_nop 0
	global_load_dwordx4 v[8:11], v[8:9], off offset:512
	v_lshl_add_u64 v[20:21], v[20:21], 2, s[8:9]
	v_lshl_add_u64 v[22:23], v[22:23], 2, s[8:9]
	v_lshl_add_u64 v[24:25], v[24:25], 2, s[8:9]
	v_lshl_add_u64 v[16:17], v[16:17], 2, s[8:9]
	global_load_dword v174, v[18:19], off
	global_load_dword v173, v[18:19], off offset:64
	global_load_dword v172, v[18:19], off offset:128
	global_load_dword v171, v[18:19], off offset:192
	global_load_dword v170, v[20:21], off
	global_load_dword v169, v[22:23], off
	global_load_dword v168, v[24:25], off
	global_load_dword v167, v[16:17], off
	s_andn2_b64 vcc, exec, s[6:7]
	s_cbranch_vccnz .LBB0_939
	s_barrier
	s_branch .LBB0_939
